# v30: v29 + xor-32 reductions of the prompt attention softmax by v_permlane32_swap instead of ds_bpermute
# baseline (speedup 1.0000x reference)
; DI float fexp2(float x) { return __builtin_amdgcn_exp2f(x); }
; DI bf16x8 pack_step(const f32x16& x, int s) { u32x4 p; p.x = pk2(x[8 * s], x[8 * s + 1]); p.y = pk2(x[8 * s + 2], x[8 * s + 3]); p.z = pk2(x[8 * s + 4], x[8 * s + 5]); p.w = pk2(x[8 * s + 6], x[8 * s + 7]); return __builtin_bit_cast(bf16x8, p); }
; #define MFMA32(a, b, c) __builtin_amdgcn_mfma_f32_32x32x16_bf16((a), (b), (c), 0, 0, 0)
; template <class T> DI void attn_item(const T& t) {
;     ...
;         float ps = 0.f;
; #pragma unroll
;         for (int i = 0; i < 16; ++i) { const float p = fexp2(s[i] - m); s[i] = p; ps += p; }
;         ps += __shfl_xor(ps, 32);
;         l += ps;
; #pragma unroll
;         for (int s2 = 0; s2 < 2; ++s2) { const bf16x8 pb = pack_step(s, s2);
;             if (T::VSPLIT) {
; #pragma unroll
;                 for (int dd = 0; dd < D / 32; ++dd) vf[s2][dd] = t.vfrag_t(tl, s2, dd);
;             }
; #pragma unroll
;             for (int dd = 0; dd < D / 32; ++dd) o[dd] = MFMA32(vf[s2][dd], pb, o[dd]); }
.LBB0_971:
	s_cmp_eq_u32 s79, s40
	s_cbranch_scc1 .Latt_sw3_last
	v_sub_f32_e32 v36, v36, v126
	v_exp_f32_e32 v36, v36
	v_sub_f32_e32 v37, v37, v126
	v_exp_f32_e32 v37, v37
	v_sub_f32_e32 v38, v38, v126
	v_exp_f32_e32 v38, v38
	v_sub_f32_e32 v39, v39, v126
	v_exp_f32_e32 v39, v39
	v_sub_f32_e32 v40, v40, v126
	v_add_f32_e32 v127, 0, v36
	v_exp_f32_e32 v40, v40
	v_sub_f32_e32 v41, v41, v126
	v_add_f32_e32 v127, v37, v127
	v_exp_f32_e32 v41, v41
	v_sub_f32_e32 v42, v42, v126
	v_sub_f32_e32 v43, v43, v126
	v_add_f32_e32 v127, v38, v127
	v_exp_f32_e32 v42, v42
	v_exp_f32_e32 v43, v43
	v_add_f32_e32 v127, v39, v127
	v_sub_f32_e32 v44, v44, v126
	v_add_f32_e32 v127, v40, v127
	v_exp_f32_e32 v44, v44
	v_sub_f32_e32 v45, v45, v126
	v_add_f32_e32 v127, v41, v127
	v_exp_f32_e32 v45, v45
	v_sub_f32_e32 v46, v46, v126
	v_add_f32_e32 v127, v42, v127
	v_exp_f32_e32 v46, v46
	v_sub_f32_e32 v47, v47, v126
	v_cvt_pk_bf16_f32 v36, v36, v37
	v_cvt_pk_bf16_f32 v37, v38, v39
	v_cvt_pk_bf16_f32 v38, v40, v41
	v_cvt_pk_bf16_f32 v39, v42, v43
	v_add_f32_e32 v127, v43, v127
	v_exp_f32_e32 v47, v47
	v_sub_f32_e32 v48, v48, v126
	s_waitcnt vmcnt(7)
	v_mfma_f32_32x32x16_bf16 v[20:35], v[96:99], v[36:39], v[20:35]
	v_add_f32_e32 v127, v44, v127
	v_exp_f32_e32 v40, v48
	v_sub_f32_e32 v41, v49, v126
	v_add_f32_e32 v127, v45, v127
	v_exp_f32_e32 v41, v41
	v_sub_f32_e32 v42, v50, v126
	v_add_f32_e32 v127, v46, v127
	s_waitcnt vmcnt(6)
	v_mfma_f32_32x32x16_bf16 v[4:19], v[92:95], v[36:39], v[4:19]
	v_sub_f32_e32 v36, v51, v126
	v_exp_f32_e32 v42, v42
	v_exp_f32_e32 v48, v36
	v_add_f32_e32 v127, v47, v127
	v_add_f32_e32 v43, v40, v127
	v_add_f32_e32 v43, v41, v43
	v_add_f32_e32 v43, v42, v43
	v_cvt_pk_bf16_f32 v36, v44, v45
	v_cvt_pk_bf16_f32 v37, v46, v47
	v_cvt_pk_bf16_f32 v38, v40, v41
	v_cvt_pk_bf16_f32 v39, v42, v48
	v_add_f32_e32 v40, v48, v43
	v_mov_b32_e32 v41, v40
	s_nop 1
	v_permlane32_swap_b32 v41, v40
	s_waitcnt vmcnt(5)
	v_mfma_f32_32x32x16_bf16 v[20:35], v[88:91], v[36:39], v[20:35]
	s_add_u32 s40, s40, 0x1000
	s_addc_u32 s41, s41, 0
	s_add_i32 s72, s72, 32
	s_waitcnt lgkmcnt(0)
	v_add_f32_e32 v40, v40, v41
	s_cmp_eq_u32 s86, s40
	v_add_f32_e32 v125, v125, v40
	s_waitcnt vmcnt(4)
	v_mfma_f32_32x32x16_bf16 v[4:19], v[84:87], v[36:39], v[4:19]
	s_branch .LBB0_972
.Latt_sw3_last:
	v_sub_f32_e32 v36, v36, v126
	v_exp_f32_e32 v36, v36
	v_sub_f32_e32 v37, v37, v126
	v_exp_f32_e32 v37, v37
	v_sub_f32_e32 v38, v38, v126
	v_exp_f32_e32 v38, v38
	v_sub_f32_e32 v39, v39, v126
	v_exp_f32_e32 v39, v39
	v_sub_f32_e32 v40, v40, v126
	v_add_f32_e32 v127, 0, v36
	v_exp_f32_e32 v40, v40
	v_sub_f32_e32 v41, v41, v126
	v_add_f32_e32 v127, v37, v127
	v_exp_f32_e32 v41, v41
	v_sub_f32_e32 v42, v42, v126
	v_sub_f32_e32 v43, v43, v126
	v_add_f32_e32 v127, v38, v127
	v_exp_f32_e32 v42, v42
	v_exp_f32_e32 v43, v43
	v_add_f32_e32 v127, v39, v127
	v_sub_f32_e32 v44, v44, v126
	v_add_f32_e32 v127, v40, v127
	v_exp_f32_e32 v44, v44
	v_sub_f32_e32 v45, v45, v126
	v_add_f32_e32 v127, v41, v127
	v_exp_f32_e32 v45, v45
	v_sub_f32_e32 v46, v46, v126
	v_add_f32_e32 v127, v42, v127
	v_exp_f32_e32 v46, v46
	v_sub_f32_e32 v47, v47, v126
	v_cvt_pk_bf16_f32 v36, v36, v37
	v_cvt_pk_bf16_f32 v37, v38, v39
	v_cvt_pk_bf16_f32 v38, v40, v41
	v_cvt_pk_bf16_f32 v39, v42, v43
	v_add_f32_e32 v127, v43, v127
	v_exp_f32_e32 v47, v47
	v_sub_f32_e32 v48, v48, v126
	s_waitcnt vmcnt(3)
	v_mfma_f32_32x32x16_bf16 v[20:35], v[96:99], v[36:39], v[20:35]
	v_add_f32_e32 v127, v44, v127
	v_exp_f32_e32 v40, v48
	v_sub_f32_e32 v41, v49, v126
	v_add_f32_e32 v127, v45, v127
	v_exp_f32_e32 v41, v41
	v_sub_f32_e32 v42, v50, v126
	v_add_f32_e32 v127, v46, v127
	s_waitcnt vmcnt(2)
	v_mfma_f32_32x32x16_bf16 v[4:19], v[92:95], v[36:39], v[4:19]
	v_sub_f32_e32 v36, v51, v126
	v_exp_f32_e32 v42, v42
	v_exp_f32_e32 v48, v36
	v_add_f32_e32 v127, v47, v127
	v_add_f32_e32 v43, v40, v127
	v_add_f32_e32 v43, v41, v43
	v_add_f32_e32 v43, v42, v43
	v_cvt_pk_bf16_f32 v36, v44, v45
	v_cvt_pk_bf16_f32 v37, v46, v47
	v_cvt_pk_bf16_f32 v38, v40, v41
	v_cvt_pk_bf16_f32 v39, v42, v48
	v_add_f32_e32 v40, v48, v43
	v_mov_b32_e32 v41, v40
	s_nop 1
	v_permlane32_swap_b32 v41, v40
	s_waitcnt vmcnt(1)
	v_mfma_f32_32x32x16_bf16 v[20:35], v[88:91], v[36:39], v[20:35]
	s_add_u32 s40, s40, 0x1000
	s_addc_u32 s41, s41, 0
	s_add_i32 s72, s72, 32
	s_waitcnt lgkmcnt(0)
	v_add_f32_e32 v40, v40, v41
	s_cmp_eq_u32 s86, s40
	v_add_f32_e32 v125, v125, v40
	s_waitcnt vmcnt(0)
	v_mfma_f32_32x32x16_bf16 v[4:19], v[84:87], v[36:39], v[4:19]
	s_cbranch_scc1 .LBB0_979

; DI float fexp2(float x) { return __builtin_amdgcn_exp2f(x); }
; template <class T> DI void attn_item(const T& t) {
;     ...
;         float mx = s[0];
; #pragma unroll
;         for (int i = 1; i < 16; ++i) mx = fmaxf(mx, s[i]);
;         mx = fmaxf(mx, __shfl_xor(mx, 32));
;         const bool need = mx > m + 8.0f;
;         if (__builtin_amdgcn_ballot_w64(need) != 0ull) {
;             const float mn = need ? mx : m;
;             const float sc = fexp2(m - mn);
;             l *= sc; m = mn;
; #pragma unroll
;             for (int dd = 0; dd < D / 32; ++dd)
; #pragma unroll
;                 for (int i = 0; i < 16; ++i) o[dd][i] *= sc;
;         }
.LBB0_977:
	s_nop 8
	v_max_f32_e32 v127, v37, v37
	v_max_f32_e32 v128, v36, v36
	v_max_f32_e32 v127, v128, v127
	v_max3_f32 v127, v127, v38, v39
	v_max3_f32 v127, v127, v40, v41
	v_max3_f32 v127, v127, v42, v43
	v_max3_f32 v127, v127, v44, v45
	v_max3_f32 v127, v127, v46, v47
	v_max3_f32 v127, v127, v48, v49
	v_max3_f32 v127, v127, v50, v51
	v_mov_b32_e32 v128, v127
	s_nop 1
	v_permlane32_swap_b32 v128, v127
	v_max_f32_e32 v127, v127, v128
	v_add_f32_e32 v128, 0x41000000, v126
	v_cmp_gt_f32_e32 vcc, v127, v128
	s_cbranch_vccz .LBB0_971
	s_nop 0
	v_cndmask_b32_e32 v127, v126, v127, vcc
	v_sub_f32_e32 v126, v126, v127
	v_exp_f32_e32 v126, v126
	s_nop 0
	v_pk_mul_f32 v[34:35], v[34:35], v[126:127] op_sel_hi:[1,0]
	v_pk_mul_f32 v[32:33], v[32:33], v[126:127] op_sel_hi:[1,0]
	v_pk_mul_f32 v[30:31], v[30:31], v[126:127] op_sel_hi:[1,0]
	v_pk_mul_f32 v[28:29], v[28:29], v[126:127] op_sel_hi:[1,0]
	v_pk_mul_f32 v[26:27], v[26:27], v[126:127] op_sel_hi:[1,0]
	v_pk_mul_f32 v[24:25], v[24:25], v[126:127] op_sel_hi:[1,0]
	v_pk_mul_f32 v[22:23], v[22:23], v[126:127] op_sel_hi:[1,0]
	v_pk_mul_f32 v[20:21], v[20:21], v[126:127] op_sel_hi:[1,0]
	v_pk_mul_f32 v[18:19], v[18:19], v[126:127] op_sel_hi:[1,0]
	v_pk_mul_f32 v[16:17], v[16:17], v[126:127] op_sel_hi:[1,0]
	v_pk_mul_f32 v[14:15], v[14:15], v[126:127] op_sel_hi:[1,0]
	v_pk_mul_f32 v[12:13], v[12:13], v[126:127] op_sel_hi:[1,0]
	v_pk_mul_f32 v[10:11], v[10:11], v[126:127] op_sel_hi:[1,0]
	v_pk_mul_f32 v[8:9], v[8:9], v[126:127] op_sel_hi:[1,0]
	v_pk_mul_f32 v[6:7], v[6:7], v[126:127] op_sel_hi:[1,0]
	v_pk_mul_f32 v[4:5], v[4:5], v[126:127] op_sel_hi:[1,0]
	v_mul_f32_e32 v125, v125, v126
	v_mov_b32_e32 v126, v127
	s_branch .LBB0_971

; DI float fexp2(float x) { return __builtin_amdgcn_exp2f(x); }
; DI bf16x8 pack_step(const f32x16& x, int s) { u32x4 p; p.x = pk2(x[8 * s], x[8 * s + 1]); p.y = pk2(x[8 * s + 2], x[8 * s + 3]); p.z = pk2(x[8 * s + 4], x[8 * s + 5]); p.w = pk2(x[8 * s + 6], x[8 * s + 7]); return __builtin_bit_cast(bf16x8, p); }
; #define MFMA32(a, b, c) __builtin_amdgcn_mfma_f32_32x32x16_bf16((a), (b), (c), 0, 0, 0)
; template <class T> DI void attn_item(const T& t) {
;     ...
;         float ps = 0.f;
; #pragma unroll
;         for (int i = 0; i < 16; ++i) { const float p = fexp2(s[i] - m); s[i] = p; ps += p; }
;         ps += __shfl_xor(ps, 32);
;         l += ps;
; #pragma unroll
;         for (int s2 = 0; s2 < 2; ++s2) { const bf16x8 pb = pack_step(s, s2);
;             if (T::VSPLIT) {
; #pragma unroll
;                 for (int dd = 0; dd < D / 32; ++dd) vf[s2][dd] = t.vfrag_t(tl, s2, dd);
;             }
; #pragma unroll
;             for (int dd = 0; dd < D / 32; ++dd) o[dd] = MFMA32(vf[s2][dd], pb, o[dd]); }
.LBB0_982:
	s_cmpk_eq_u32 s40, 0xe000
	s_cbranch_scc1 .Latt_mm3_last
	v_sub_f32_e32 v2, v82, v224
	v_sub_f32_e32 v16, v83, v224
	v_sub_f32_e32 v82, v85, v224
	v_exp_f32_e32 v2, v2
	v_exp_f32_e32 v16, v16
	v_exp_f32_e32 v225, v82
	v_sub_f32_e32 v82, v86, v224
	v_sub_f32_e32 v17, v84, v224
	v_exp_f32_e32 v86, v82
	v_sub_f32_e32 v82, v87, v224
	v_exp_f32_e32 v17, v17
	v_exp_f32_e32 v87, v82
	v_sub_f32_e32 v82, v88, v224
	v_exp_f32_e32 v88, v82
	v_sub_f32_e32 v82, v89, v224
	v_exp_f32_e32 v89, v82
	v_cvt_pk_bf16_f32 v82, v2, v16
	v_add_f32_e32 v2, 0, v2
	v_add_f32_e32 v2, v16, v2
	v_add_f32_e32 v2, v17, v2
	v_sub_f32_e32 v90, v90, v224
	v_add_f32_e32 v2, v225, v2
	v_exp_f32_e32 v90, v90
	v_sub_f32_e32 v91, v91, v224
	v_add_f32_e32 v2, v86, v2
	v_exp_f32_e32 v91, v91
	v_sub_f32_e32 v92, v92, v224
	v_add_f32_e32 v2, v87, v2
	v_cvt_pk_bf16_f32 v83, v17, v225
	v_cvt_pk_bf16_f32 v84, v86, v87
	v_cvt_pk_bf16_f32 v85, v88, v89
	v_exp_f32_e32 v92, v92
	v_sub_f32_e32 v93, v93, v224
	v_add_f32_e32 v2, v88, v2
	s_waitcnt vmcnt(13)
	v_mfma_f32_32x32x16_bf16 v[66:81], v[178:181], v[82:85], v[66:81]
	v_exp_f32_e32 v93, v93
	v_sub_f32_e32 v94, v94, v224
	v_add_f32_e32 v2, v89, v2
	v_exp_f32_e32 v94, v94
	v_sub_f32_e32 v95, v95, v224
	v_add_f32_e32 v2, v90, v2
	v_exp_f32_e32 v95, v95
	v_mfma_f32_32x32x16_bf16 v[50:65], v[174:177], v[82:85], v[50:65]
	v_sub_f32_e32 v96, v96, v224
	v_add_f32_e32 v2, v91, v2
	v_exp_f32_e32 v96, v96
	v_add_f32_e32 v2, v92, v2
	v_add_f32_e32 v2, v93, v2
	v_add_f32_e32 v2, v94, v2
	v_add_f32_e32 v2, v95, v2
	v_mfma_f32_32x32x16_bf16 v[34:49], v[170:173], v[82:85], v[34:49]
	v_add_f32_e32 v2, v96, v2
	s_add_u32 s40, s40, 0x2000
	s_addc_u32 s41, s41, 0
	s_cmp_eq_u32 s40, 0x10000
	s_waitcnt vmcnt(12)
	v_mfma_f32_32x32x16_bf16 v[18:33], v[166:169], v[82:85], v[18:33]
	v_sub_f32_e32 v82, v97, v224
	v_exp_f32_e32 v97, v82
	v_cvt_pk_bf16_f32 v82, v90, v91
	v_cvt_pk_bf16_f32 v83, v92, v93
	v_cvt_pk_bf16_f32 v84, v94, v95
	v_cvt_pk_bf16_f32 v85, v96, v97
	v_add_f32_e32 v2, v97, v2
	s_waitcnt vmcnt(11)
	v_mfma_f32_32x32x16_bf16 v[66:81], v[162:165], v[82:85], v[66:81]
	s_waitcnt vmcnt(10)
	v_mfma_f32_32x32x16_bf16 v[50:65], v[12:15], v[82:85], v[50:65]
	s_waitcnt vmcnt(9)
	v_mfma_f32_32x32x16_bf16 v[34:49], v[8:11], v[82:85], v[34:49]
	v_mov_b32_e32 v240, v2
	s_nop 1
	v_permlane32_swap_b32 v240, v2
	v_add_f32_e32 v2, v2, v240
	v_add_f32_e32 v223, v223, v2
	s_waitcnt vmcnt(8)
	v_mfma_f32_32x32x16_bf16 v[18:33], v[4:7], v[82:85], v[18:33]
	s_branch .LBB0_983
.Latt_mm3_last:
	v_sub_f32_e32 v2, v82, v224
	v_sub_f32_e32 v16, v83, v224
	v_sub_f32_e32 v82, v85, v224
	v_exp_f32_e32 v2, v2
	v_exp_f32_e32 v16, v16
	v_exp_f32_e32 v225, v82
	v_sub_f32_e32 v82, v86, v224
	v_sub_f32_e32 v17, v84, v224
	v_exp_f32_e32 v86, v82
	v_sub_f32_e32 v82, v87, v224
	v_exp_f32_e32 v17, v17
	v_exp_f32_e32 v87, v82
	v_sub_f32_e32 v82, v88, v224
	v_exp_f32_e32 v88, v82
	v_sub_f32_e32 v82, v89, v224
	v_exp_f32_e32 v89, v82
	v_cvt_pk_bf16_f32 v82, v2, v16
	v_add_f32_e32 v2, 0, v2
	v_add_f32_e32 v2, v16, v2
	v_add_f32_e32 v2, v17, v2
	v_sub_f32_e32 v90, v90, v224
	v_add_f32_e32 v2, v225, v2
	v_exp_f32_e32 v90, v90
	v_sub_f32_e32 v91, v91, v224
	v_add_f32_e32 v2, v86, v2
	v_exp_f32_e32 v91, v91
	v_sub_f32_e32 v92, v92, v224
	v_add_f32_e32 v2, v87, v2
	v_cvt_pk_bf16_f32 v83, v17, v225
	v_cvt_pk_bf16_f32 v84, v86, v87
	v_cvt_pk_bf16_f32 v85, v88, v89
	v_exp_f32_e32 v92, v92
	v_sub_f32_e32 v93, v93, v224
	v_add_f32_e32 v2, v88, v2
	s_waitcnt vmcnt(5)
	v_mfma_f32_32x32x16_bf16 v[66:81], v[178:181], v[82:85], v[66:81]
	v_exp_f32_e32 v93, v93
	v_sub_f32_e32 v94, v94, v224
	v_add_f32_e32 v2, v89, v2
	v_exp_f32_e32 v94, v94
	v_sub_f32_e32 v95, v95, v224
	v_add_f32_e32 v2, v90, v2
	v_exp_f32_e32 v95, v95
	v_mfma_f32_32x32x16_bf16 v[50:65], v[174:177], v[82:85], v[50:65]
	v_sub_f32_e32 v96, v96, v224
	v_add_f32_e32 v2, v91, v2
	v_exp_f32_e32 v96, v96
	v_add_f32_e32 v2, v92, v2
	v_add_f32_e32 v2, v93, v2
	v_add_f32_e32 v2, v94, v2
	v_add_f32_e32 v2, v95, v2
	v_mfma_f32_32x32x16_bf16 v[34:49], v[170:173], v[82:85], v[34:49]
	v_add_f32_e32 v2, v96, v2
	s_add_u32 s40, s40, 0x2000
	s_addc_u32 s41, s41, 0
	s_cmp_eq_u32 s40, 0x10000
	s_waitcnt vmcnt(4)
	v_mfma_f32_32x32x16_bf16 v[18:33], v[166:169], v[82:85], v[18:33]
	v_sub_f32_e32 v82, v97, v224
	v_exp_f32_e32 v97, v82
	v_cvt_pk_bf16_f32 v82, v90, v91
	v_cvt_pk_bf16_f32 v83, v92, v93
	v_cvt_pk_bf16_f32 v84, v94, v95
	v_cvt_pk_bf16_f32 v85, v96, v97
	v_add_f32_e32 v2, v97, v2
	s_waitcnt vmcnt(3)
	v_mfma_f32_32x32x16_bf16 v[66:81], v[162:165], v[82:85], v[66:81]
	s_waitcnt vmcnt(2)
	v_mfma_f32_32x32x16_bf16 v[50:65], v[12:15], v[82:85], v[50:65]
	s_waitcnt vmcnt(1)
	v_mfma_f32_32x32x16_bf16 v[34:49], v[8:11], v[82:85], v[34:49]
	v_mov_b32_e32 v240, v2
	s_nop 1
	v_permlane32_swap_b32 v240, v2
	v_add_f32_e32 v2, v2, v240
	v_add_f32_e32 v223, v223, v2
	s_waitcnt vmcnt(0)
	v_mfma_f32_32x32x16_bf16 v[18:33], v[4:7], v[82:85], v[18:33]
	s_cbranch_scc1 .LBB0_957

; DI float fexp2(float x) { return __builtin_amdgcn_exp2f(x); }
; template <class T> DI void attn_item(const T& t) {
;     ...
;         float mx = s[0];
; #pragma unroll
;         for (int i = 1; i < 16; ++i) mx = fmaxf(mx, s[i]);
;         mx = fmaxf(mx, __shfl_xor(mx, 32));
;         const bool need = mx > m + 8.0f;
;         if (__builtin_amdgcn_ballot_w64(need) != 0ull) {
;             const float mn = need ? mx : m;
;             const float sc = fexp2(m - mn);
;             l *= sc; m = mn;
; #pragma unroll
;             for (int dd = 0; dd < D / 32; ++dd)
; #pragma unroll
;                 for (int i = 0; i < 16; ++i) o[dd][i] *= sc;
;         }
.LBB0_985:
	s_nop 10
	v_max_f32_e32 v2, v83, v83
	v_max_f32_e32 v16, v82, v82
	v_max_f32_e32 v2, v16, v2
	v_max3_f32 v2, v2, v84, v85
	v_max3_f32 v2, v2, v86, v87
	v_max3_f32 v2, v2, v88, v89
	v_max3_f32 v2, v2, v90, v91
	v_max3_f32 v2, v2, v92, v93
	v_max3_f32 v2, v2, v94, v95
	v_max3_f32 v2, v2, v96, v97
	v_mov_b32_e32 v16, v2
	s_nop 1
	v_permlane32_swap_b32 v16, v2
	v_max_f32_e32 v2, v2, v16
	v_add_f32_e32 v16, 0x41000000, v224
	v_cmp_gt_f32_e32 vcc, v2, v16
	s_cbranch_vccz .LBB0_982
	s_nop 0
	v_cndmask_b32_e32 v16, v224, v2, vcc
	v_sub_f32_e32 v2, v224, v16
	v_exp_f32_e32 v2, v2
	v_mov_b32_e32 v224, v16
	v_pk_mul_f32 v[80:81], v[80:81], v[2:3] op_sel_hi:[1,0]
	v_pk_mul_f32 v[78:79], v[78:79], v[2:3] op_sel_hi:[1,0]
	v_pk_mul_f32 v[76:77], v[76:77], v[2:3] op_sel_hi:[1,0]
	v_pk_mul_f32 v[74:75], v[74:75], v[2:3] op_sel_hi:[1,0]
	v_pk_mul_f32 v[72:73], v[72:73], v[2:3] op_sel_hi:[1,0]
	v_pk_mul_f32 v[70:71], v[70:71], v[2:3] op_sel_hi:[1,0]
	v_pk_mul_f32 v[68:69], v[68:69], v[2:3] op_sel_hi:[1,0]
	v_pk_mul_f32 v[66:67], v[66:67], v[2:3] op_sel_hi:[1,0]
	v_pk_mul_f32 v[64:65], v[64:65], v[2:3] op_sel_hi:[1,0]
	v_pk_mul_f32 v[62:63], v[62:63], v[2:3] op_sel_hi:[1,0]
	v_pk_mul_f32 v[60:61], v[60:61], v[2:3] op_sel_hi:[1,0]
	v_pk_mul_f32 v[58:59], v[58:59], v[2:3] op_sel_hi:[1,0]
	v_pk_mul_f32 v[56:57], v[56:57], v[2:3] op_sel_hi:[1,0]
	v_pk_mul_f32 v[54:55], v[54:55], v[2:3] op_sel_hi:[1,0]
	v_pk_mul_f32 v[52:53], v[52:53], v[2:3] op_sel_hi:[1,0]
	v_pk_mul_f32 v[50:51], v[50:51], v[2:3] op_sel_hi:[1,0]
	v_pk_mul_f32 v[48:49], v[48:49], v[2:3] op_sel_hi:[1,0]
	v_pk_mul_f32 v[46:47], v[46:47], v[2:3] op_sel_hi:[1,0]
	v_pk_mul_f32 v[44:45], v[44:45], v[2:3] op_sel_hi:[1,0]
	v_pk_mul_f32 v[42:43], v[42:43], v[2:3] op_sel_hi:[1,0]
	v_pk_mul_f32 v[40:41], v[40:41], v[2:3] op_sel_hi:[1,0]
	v_pk_mul_f32 v[38:39], v[38:39], v[2:3] op_sel_hi:[1,0]
	v_pk_mul_f32 v[36:37], v[36:37], v[2:3] op_sel_hi:[1,0]
	v_pk_mul_f32 v[34:35], v[34:35], v[2:3] op_sel_hi:[1,0]
	v_pk_mul_f32 v[32:33], v[32:33], v[2:3] op_sel_hi:[1,0]
	v_pk_mul_f32 v[30:31], v[30:31], v[2:3] op_sel_hi:[1,0]
	v_pk_mul_f32 v[28:29], v[28:29], v[2:3] op_sel_hi:[1,0]
	v_pk_mul_f32 v[26:27], v[26:27], v[2:3] op_sel_hi:[1,0]
	v_pk_mul_f32 v[24:25], v[24:25], v[2:3] op_sel_hi:[1,0]
	v_pk_mul_f32 v[22:23], v[22:23], v[2:3] op_sel_hi:[1,0]
	v_pk_mul_f32 v[20:21], v[20:21], v[2:3] op_sel_hi:[1,0]
	v_pk_mul_f32 v[18:19], v[18:19], v[2:3] op_sel_hi:[1,0]
	v_mul_f32_e32 v223, v223, v2
	s_branch .LBB0_982

; DI float fexp2(float x) { return __builtin_amdgcn_exp2f(x); }
; DI bf16x8 pack_step(const f32x16& x, int s) { u32x4 p; p.x = pk2(x[8 * s], x[8 * s + 1]); p.y = pk2(x[8 * s + 2], x[8 * s + 3]); p.z = pk2(x[8 * s + 4], x[8 * s + 5]); p.w = pk2(x[8 * s + 6], x[8 * s + 7]); return __builtin_bit_cast(bf16x8, p); }
; #define MFMA32(a, b, c) __builtin_amdgcn_mfma_f32_32x32x16_bf16((a), (b), (c), 0, 0, 0)
; template <class T> DI void attn_item(const T& t) {
;     ...
;         float ps = 0.f;
; #pragma unroll
;         for (int i = 0; i < 16; ++i) { const float p = fexp2(s[i] - m); s[i] = p; ps += p; }
;         ps += __shfl_xor(ps, 32);
;         l += ps;
; #pragma unroll
;         for (int s2 = 0; s2 < 2; ++s2) { const bf16x8 pb = pack_step(s, s2);
;             if (T::VSPLIT) {
; #pragma unroll
;                 for (int dd = 0; dd < D / 32; ++dd) vf[s2][dd] = t.vfrag_t(tl, s2, dd);
;             }
; #pragma unroll
;             for (int dd = 0; dd < D / 32; ++dd) o[dd] = MFMA32(vf[s2][dd], pb, o[dd]); }
.LBB0_1081:
	s_cmp_eq_u32 s77, s40
	s_cbranch_scc1 .Latt_sw4_last
	v_sub_f32_e32 v36, v36, v126
	v_exp_f32_e32 v36, v36
	v_sub_f32_e32 v37, v37, v126
	v_exp_f32_e32 v37, v37
	v_sub_f32_e32 v38, v38, v126
	v_exp_f32_e32 v38, v38
	v_sub_f32_e32 v39, v39, v126
	v_exp_f32_e32 v39, v39
	v_sub_f32_e32 v40, v40, v126
	v_add_f32_e32 v127, 0, v36
	v_exp_f32_e32 v40, v40
	v_sub_f32_e32 v41, v41, v126
	v_add_f32_e32 v127, v37, v127
	v_exp_f32_e32 v41, v41
	v_sub_f32_e32 v42, v42, v126
	v_sub_f32_e32 v43, v43, v126
	v_add_f32_e32 v127, v38, v127
	v_exp_f32_e32 v42, v42
	v_exp_f32_e32 v43, v43
	v_add_f32_e32 v127, v39, v127
	v_sub_f32_e32 v44, v44, v126
	v_add_f32_e32 v127, v40, v127
	v_exp_f32_e32 v44, v44
	v_sub_f32_e32 v45, v45, v126
	v_add_f32_e32 v127, v41, v127
	v_exp_f32_e32 v45, v45
	v_sub_f32_e32 v46, v46, v126
	v_add_f32_e32 v127, v42, v127
	v_exp_f32_e32 v46, v46
	v_sub_f32_e32 v47, v47, v126
	v_cvt_pk_bf16_f32 v36, v36, v37
	v_cvt_pk_bf16_f32 v37, v38, v39
	v_cvt_pk_bf16_f32 v38, v40, v41
	v_cvt_pk_bf16_f32 v39, v42, v43
	v_add_f32_e32 v127, v43, v127
	v_exp_f32_e32 v47, v47
	v_sub_f32_e32 v48, v48, v126
	s_waitcnt vmcnt(7)
	v_mfma_f32_32x32x16_bf16 v[20:35], v[96:99], v[36:39], v[20:35]
	v_add_f32_e32 v127, v44, v127
	v_exp_f32_e32 v40, v48
	v_sub_f32_e32 v41, v49, v126
	v_add_f32_e32 v127, v45, v127
	v_exp_f32_e32 v41, v41
	v_sub_f32_e32 v42, v50, v126
	v_add_f32_e32 v127, v46, v127
	s_waitcnt vmcnt(6)
	v_mfma_f32_32x32x16_bf16 v[4:19], v[92:95], v[36:39], v[4:19]
	v_sub_f32_e32 v36, v51, v126
	v_exp_f32_e32 v42, v42
	v_exp_f32_e32 v48, v36
	v_add_f32_e32 v127, v47, v127
	v_add_f32_e32 v43, v40, v127
	v_add_f32_e32 v43, v41, v43
	v_add_f32_e32 v43, v42, v43
	v_cvt_pk_bf16_f32 v36, v44, v45
	v_cvt_pk_bf16_f32 v37, v46, v47
	v_cvt_pk_bf16_f32 v38, v40, v41
	v_cvt_pk_bf16_f32 v39, v42, v48
	v_add_f32_e32 v40, v48, v43
	v_mov_b32_e32 v41, v40
	s_nop 1
	v_permlane32_swap_b32 v41, v40
	s_waitcnt vmcnt(5)
	v_mfma_f32_32x32x16_bf16 v[20:35], v[88:91], v[36:39], v[20:35]
	s_add_u32 s40, s40, 0x1000
	s_addc_u32 s41, s41, 0
	s_add_i32 s74, s74, 32
	s_waitcnt lgkmcnt(0)
	v_add_f32_e32 v40, v40, v41
	s_cmp_eq_u32 s84, s40
	v_add_f32_e32 v125, v125, v40
	s_waitcnt vmcnt(4)
	v_mfma_f32_32x32x16_bf16 v[4:19], v[84:87], v[36:39], v[4:19]
	s_branch .LBB0_1082
.Latt_sw4_last:
	v_sub_f32_e32 v36, v36, v126
	v_exp_f32_e32 v36, v36
	v_sub_f32_e32 v37, v37, v126
	v_exp_f32_e32 v37, v37
	v_sub_f32_e32 v38, v38, v126
	v_exp_f32_e32 v38, v38
	v_sub_f32_e32 v39, v39, v126
	v_exp_f32_e32 v39, v39
	v_sub_f32_e32 v40, v40, v126
	v_add_f32_e32 v127, 0, v36
	v_exp_f32_e32 v40, v40
	v_sub_f32_e32 v41, v41, v126
	v_add_f32_e32 v127, v37, v127
	v_exp_f32_e32 v41, v41
	v_sub_f32_e32 v42, v42, v126
	v_sub_f32_e32 v43, v43, v126
	v_add_f32_e32 v127, v38, v127
	v_exp_f32_e32 v42, v42
	v_exp_f32_e32 v43, v43
	v_add_f32_e32 v127, v39, v127
	v_sub_f32_e32 v44, v44, v126
	v_add_f32_e32 v127, v40, v127
	v_exp_f32_e32 v44, v44
	v_sub_f32_e32 v45, v45, v126
	v_add_f32_e32 v127, v41, v127
	v_exp_f32_e32 v45, v45
	v_sub_f32_e32 v46, v46, v126
	v_add_f32_e32 v127, v42, v127
	v_exp_f32_e32 v46, v46
	v_sub_f32_e32 v47, v47, v126
	v_cvt_pk_bf16_f32 v36, v36, v37
	v_cvt_pk_bf16_f32 v37, v38, v39
	v_cvt_pk_bf16_f32 v38, v40, v41
	v_cvt_pk_bf16_f32 v39, v42, v43
	v_add_f32_e32 v127, v43, v127
	v_exp_f32_e32 v47, v47
	v_sub_f32_e32 v48, v48, v126
	s_waitcnt vmcnt(3)
	v_mfma_f32_32x32x16_bf16 v[20:35], v[96:99], v[36:39], v[20:35]
	v_add_f32_e32 v127, v44, v127
	v_exp_f32_e32 v40, v48
	v_sub_f32_e32 v41, v49, v126
	v_add_f32_e32 v127, v45, v127
	v_exp_f32_e32 v41, v41
	v_sub_f32_e32 v42, v50, v126
	v_add_f32_e32 v127, v46, v127
	s_waitcnt vmcnt(2)
	v_mfma_f32_32x32x16_bf16 v[4:19], v[92:95], v[36:39], v[4:19]
	v_sub_f32_e32 v36, v51, v126
	v_exp_f32_e32 v42, v42
	v_exp_f32_e32 v48, v36
	v_add_f32_e32 v127, v47, v127
	v_add_f32_e32 v43, v40, v127
	v_add_f32_e32 v43, v41, v43
	v_add_f32_e32 v43, v42, v43
	v_cvt_pk_bf16_f32 v36, v44, v45
	v_cvt_pk_bf16_f32 v37, v46, v47
	v_cvt_pk_bf16_f32 v38, v40, v41
	v_cvt_pk_bf16_f32 v39, v42, v48
	v_add_f32_e32 v40, v48, v43
	v_mov_b32_e32 v41, v40
	s_nop 1
	v_permlane32_swap_b32 v41, v40
	s_waitcnt vmcnt(1)
	v_mfma_f32_32x32x16_bf16 v[20:35], v[88:91], v[36:39], v[20:35]
	s_add_u32 s40, s40, 0x1000
	s_addc_u32 s41, s41, 0
	s_add_i32 s74, s74, 32
	s_waitcnt lgkmcnt(0)
	v_add_f32_e32 v40, v40, v41
	s_cmp_eq_u32 s84, s40
	v_add_f32_e32 v125, v125, v40
	s_waitcnt vmcnt(0)
	v_mfma_f32_32x32x16_bf16 v[4:19], v[84:87], v[36:39], v[4:19]
	s_cbranch_scc1 .LBB0_1089
